# PV fragment reads one pair ahead of their MFMA (two fragment buffers) in FoX, pass B and window loops
# speedup vs baseline: 1.0125x; 1.0076x over previous
.LBB0_299:
	v_sub_f32_e32 v63, v63, v124
	v_sub_f32_e32 v62, v62, v124
	v_sub_f32_e32 v61, v61, v124
	v_sub_f32_e32 v60, v60, v124
	v_sub_f32_e32 v59, v59, v124
	v_sub_f32_e32 v58, v58, v124
	v_sub_f32_e32 v57, v57, v124
	v_sub_f32_e32 v56, v56, v124
	v_sub_f32_e32 v55, v55, v124
	v_sub_f32_e32 v54, v54, v124
	v_sub_f32_e32 v53, v53, v124
	v_sub_f32_e32 v52, v52, v124
	v_sub_f32_e32 v51, v51, v124
	v_sub_f32_e32 v50, v50, v124
	v_sub_f32_e32 v49, v49, v124
	v_sub_f32_e32 v48, v48, v124
	v_sub_f32_e32 v126, v47, v124
	v_sub_f32_e32 v127, v46, v124
	v_sub_f32_e32 v128, v45, v124
	v_sub_f32_e32 v129, v44, v124
	v_sub_f32_e32 v130, v43, v124
	v_sub_f32_e32 v131, v42, v124
	v_sub_f32_e32 v132, v41, v124
	v_sub_f32_e32 v133, v40, v124
	v_sub_f32_e32 v47, v39, v124
	v_sub_f32_e32 v39, v38, v124
	v_sub_f32_e32 v38, v37, v124
	v_sub_f32_e32 v37, v36, v124
	v_sub_f32_e32 v36, v35, v124
	v_sub_f32_e32 v35, v34, v124
	v_sub_f32_e32 v34, v33, v124
	v_sub_f32_e32 v33, v32, v124
	v_exp_f32_e32 v32, v48
	v_exp_f32_e32 v40, v33
	v_exp_f32_e32 v33, v49
	v_exp_f32_e32 v41, v34
	v_exp_f32_e32 v34, v50
	v_exp_f32_e32 v42, v35
	v_exp_f32_e32 v35, v51
	v_exp_f32_e32 v43, v36
	v_exp_f32_e32 v36, v52
	v_exp_f32_e32 v44, v37
	v_exp_f32_e32 v37, v53
	v_exp_f32_e32 v45, v38
	v_exp_f32_e32 v38, v54
	v_exp_f32_e32 v46, v39
	v_exp_f32_e32 v39, v55
	v_exp_f32_e32 v47, v47
	v_exp_f32_e32 v48, v56
	v_exp_f32_e32 v50, v133
	v_exp_f32_e32 v49, v57
	v_exp_f32_e32 v51, v132
	v_exp_f32_e32 v52, v58
	v_exp_f32_e32 v54, v131
	v_exp_f32_e32 v53, v59
	v_exp_f32_e32 v55, v130
	v_exp_f32_e32 v56, v60
	v_exp_f32_e32 v58, v129
	v_exp_f32_e32 v57, v61
	v_exp_f32_e32 v60, v62
	v_exp_f32_e32 v62, v127
	v_exp_f32_e32 v61, v63
	v_exp_f32_e32 v63, v126
	v_exp_f32_e32 v59, v128
	v_pk_add_f32 v[126:127], v[52:53], v[54:55]
	v_pk_add_f32 v[128:129], v[34:35], v[42:43]
	v_pk_add_f32 v[130:131], v[60:61], v[62:63]
	v_pk_add_f32 v[132:133], v[38:39], v[46:47]
	v_pk_add_f32 v[134:135], v[48:49], v[50:51]
	v_pk_add_f32 v[136:137], v[32:33], v[40:41]
	v_pk_add_f32 v[138:139], v[56:57], v[58:59]
	v_pk_add_f32 v[140:141], v[36:37], v[44:45]
	v_pk_add_f32 v[134:135], v[136:137], v[134:135]
	v_pk_add_f32 v[138:139], v[140:141], v[138:139]
	v_pk_add_f32 v[130:131], v[132:133], v[130:131]
	v_pk_add_f32 v[126:127], v[128:129], v[126:127]
	v_pk_add_f32 v[128:129], v[134:135], v[138:139]
	v_pk_add_f32 v[126:127], v[126:127], v[130:131]
	v_add_f32_e32 v128, v128, v129
	v_add_f32_e32 v126, v126, v127
	v_add_f32_e32 v126, v128, v126
	v_add_u32_e32 v125, s61, v116
	v_fmac_f32_e32 v126, v122, v123
	v_cvt_pk_bf16_f32 v32, v32, v33
	v_cvt_pk_bf16_f32 v33, v34, v35
	v_cvt_pk_bf16_f32 v34, v36, v37
	v_cvt_pk_bf16_f32 v35, v38, v39
	v_cvt_pk_bf16_f32 v36, v48, v49
	v_cvt_pk_bf16_f32 v37, v52, v53
	v_cvt_pk_bf16_f32 v38, v56, v57
	v_cvt_pk_bf16_f32 v39, v60, v61
	v_cvt_pk_bf16_f32 v40, v40, v41
	v_cvt_pk_bf16_f32 v41, v42, v43
	v_cvt_pk_bf16_f32 v42, v44, v45
	v_cvt_pk_bf16_f32 v43, v46, v47
	v_cvt_pk_bf16_f32 v44, v50, v51
	v_cvt_pk_bf16_f32 v45, v54, v55
	v_cvt_pk_bf16_f32 v46, v58, v59
	v_cvt_pk_bf16_f32 v47, v62, v63
	s_setprio 1
	v_add3_u32 v52, v125, v112, v117
	ds_read_b64_tr_b16 v[216:217], v52 offset:8192
	ds_read_b64_tr_b16 v[218:219], v52 offset:8704
	ds_read_b64_tr_b16 v[220:221], v52 offset:9216
	ds_read_b64_tr_b16 v[222:223], v52 offset:9728
	s_waitcnt lgkmcnt(2)
	v_mfma_f32_32x32x16_bf16 v[0:15], v[32:35], v[216:219], v[0:15]
	ds_read_b64_tr_b16 v[216:217], v52 offset:10240
	ds_read_b64_tr_b16 v[218:219], v52 offset:10752
	s_waitcnt lgkmcnt(2)
	v_mfma_f32_32x32x16_bf16 v[0:15], v[36:39], v[220:223], v[0:15]
	ds_read_b64_tr_b16 v[220:221], v52 offset:11264
	ds_read_b64_tr_b16 v[222:223], v52 offset:11776
	s_waitcnt lgkmcnt(2)
	v_mfma_f32_32x32x16_bf16 v[0:15], v[40:43], v[216:219], v[0:15]
	ds_read_b64_tr_b16 v[216:217], v52 offset:12288
	ds_read_b64_tr_b16 v[218:219], v52 offset:12800
	s_waitcnt lgkmcnt(2)
	v_mfma_f32_32x32x16_bf16 v[0:15], v[44:47], v[220:223], v[0:15]
	ds_read_b64_tr_b16 v[220:221], v52 offset:13312
	ds_read_b64_tr_b16 v[222:223], v52 offset:13824
	s_waitcnt lgkmcnt(2)
	v_mfma_f32_32x32x16_bf16 v[16:31], v[32:35], v[216:219], v[16:31]
	ds_read_b64_tr_b16 v[216:217], v52 offset:14336
	ds_read_b64_tr_b16 v[218:219], v52 offset:14848
	s_waitcnt lgkmcnt(2)
	v_mfma_f32_32x32x16_bf16 v[16:31], v[36:39], v[220:223], v[16:31]
	ds_read_b64_tr_b16 v[220:221], v52 offset:15360
	ds_read_b64_tr_b16 v[222:223], v52 offset:15872
	s_waitcnt lgkmcnt(2)
	v_mfma_f32_32x32x16_bf16 v[16:31], v[40:43], v[216:219], v[16:31]
	s_waitcnt lgkmcnt(0)
	v_mfma_f32_32x32x16_bf16 v[16:31], v[44:47], v[220:223], v[16:31]
	s_setprio 0
	s_mov_b32 s61, 0
	v_mov_b32_e32 v122, v126
	v_mov_b32_e32 v123, v124

.LBB0_3848:
	s_or_b64 exec, exec, s[12:13]
	v_cvt_pk_bf16_f32 v50, v144, v146
	s_waitcnt lgkmcnt(14)
	v_cvt_pk_bf16_f32 v51, v148, v151
	v_cvt_pk_bf16_f32 v52, v153, v155
	v_cvt_pk_bf16_f32 v53, v157, v159
	v_cvt_pk_bf16_f32 v54, v163, v165
	s_waitcnt lgkmcnt(13)
	v_cvt_pk_bf16_f32 v55, v167, v187
	v_cvt_pk_bf16_f32 v56, v189, v191
	s_waitcnt lgkmcnt(12)
	v_cvt_pk_bf16_f32 v57, v193, v195
	s_waitcnt lgkmcnt(11)
	v_cvt_pk_bf16_f32 v60, v145, v147
	v_cvt_pk_bf16_f32 v61, v150, v152
	s_waitcnt lgkmcnt(10)
	v_cvt_pk_bf16_f32 v62, v154, v156
	v_cvt_pk_bf16_f32 v63, v158, v162
	s_waitcnt lgkmcnt(9)
	v_cvt_pk_bf16_f32 v64, v164, v166
	v_cvt_pk_bf16_f32 v65, v186, v188
	s_waitcnt lgkmcnt(8)
	v_cvt_pk_bf16_f32 v66, v190, v192
	s_waitcnt lgkmcnt(6)
	v_cvt_pk_bf16_f32 v67, v194, v196
	v_add_u32_e32 v59, s20, v181
	s_setprio 1
	s_waitcnt lgkmcnt(0)
	ds_read_b64_tr_b16 v[216:217], v59 offset:8192
	ds_read_b64_tr_b16 v[218:219], v59 offset:8704
	ds_read_b64_tr_b16 v[220:221], v59 offset:9216
	ds_read_b64_tr_b16 v[222:223], v59 offset:9728
	s_waitcnt lgkmcnt(2)
	v_mfma_f32_32x32x16_bf16 v[2:17], v[50:53], v[216:219], v[2:17]
	ds_read_b64_tr_b16 v[216:217], v59 offset:10240
	ds_read_b64_tr_b16 v[218:219], v59 offset:10752
	s_waitcnt lgkmcnt(2)
	v_mfma_f32_32x32x16_bf16 v[2:17], v[54:57], v[220:223], v[2:17]
	ds_read_b64_tr_b16 v[220:221], v59 offset:11264
	ds_read_b64_tr_b16 v[222:223], v59 offset:11776
	s_waitcnt lgkmcnt(2)
	v_mfma_f32_32x32x16_bf16 v[2:17], v[60:63], v[216:219], v[2:17]
	ds_read_b64_tr_b16 v[216:217], v59 offset:12288
	ds_read_b64_tr_b16 v[218:219], v59 offset:12800
	s_waitcnt lgkmcnt(2)
	v_mfma_f32_32x32x16_bf16 v[2:17], v[64:67], v[220:223], v[2:17]
	ds_read_b64_tr_b16 v[220:221], v59 offset:13312
	ds_read_b64_tr_b16 v[222:223], v59 offset:13824
	s_waitcnt lgkmcnt(2)
	v_mfma_f32_32x32x16_bf16 v[18:33], v[50:53], v[216:219], v[18:33]
	ds_read_b64_tr_b16 v[216:217], v59 offset:14336
	ds_read_b64_tr_b16 v[218:219], v59 offset:14848
	s_waitcnt lgkmcnt(2)
	v_mfma_f32_32x32x16_bf16 v[18:33], v[54:57], v[220:223], v[18:33]
	ds_read_b64_tr_b16 v[220:221], v59 offset:15360
	ds_read_b64_tr_b16 v[222:223], v59 offset:15872
	s_waitcnt lgkmcnt(2)
	v_mfma_f32_32x32x16_bf16 v[18:33], v[60:63], v[216:219], v[18:33]
	s_waitcnt lgkmcnt(0)
	v_mfma_f32_32x32x16_bf16 v[18:33], v[64:67], v[220:223], v[18:33]
	s_setprio 0
	s_add_i32 s19, s19, 1
	s_cmp_lt_u32 s19, s15
	s_mov_b64 s[12:13], -1
	s_cbranch_scc1 .LBB0_3850
	s_add_i32 s20, s16, 0x4000
	s_mov_b64 s[12:13], 0

.LBB0_4173:
	v_sub_f32_e32 v108, v65, v1
	v_sub_f32_e32 v109, v64, v1
	v_sub_f32_e32 v110, v63, v1
	v_sub_f32_e32 v111, v62, v1
	v_sub_f32_e32 v61, v61, v1
	v_sub_f32_e32 v60, v60, v1
	v_sub_f32_e32 v59, v59, v1
	v_sub_f32_e32 v58, v58, v1
	v_sub_f32_e32 v57, v57, v1
	v_sub_f32_e32 v56, v56, v1
	v_sub_f32_e32 v55, v55, v1
	v_sub_f32_e32 v54, v54, v1
	v_sub_f32_e32 v53, v53, v1
	v_sub_f32_e32 v52, v52, v1
	v_sub_f32_e32 v51, v51, v1
	v_sub_f32_e32 v50, v50, v1
	v_sub_f32_e32 v112, v49, v1
	v_sub_f32_e32 v113, v48, v1
	v_sub_f32_e32 v114, v47, v1
	v_sub_f32_e32 v115, v46, v1
	v_sub_f32_e32 v116, v45, v1
	v_sub_f32_e32 v117, v44, v1
	v_sub_f32_e32 v65, v43, v1
	v_sub_f32_e32 v63, v42, v1
	v_sub_f32_e32 v45, v41, v1
	v_sub_f32_e32 v43, v40, v1
	v_sub_f32_e32 v41, v39, v1
	v_sub_f32_e32 v39, v38, v1
	v_sub_f32_e32 v38, v37, v1
	v_sub_f32_e32 v40, v36, v1
	v_sub_f32_e32 v37, v35, v1
	v_sub_f32_e32 v35, v34, v1
	v_exp_f32_e32 v34, v50
	v_exp_f32_e32 v36, v35
	v_exp_f32_e32 v35, v51
	v_exp_f32_e32 v37, v37
	v_exp_f32_e32 v46, v52
	v_exp_f32_e32 v48, v40
	v_exp_f32_e32 v47, v53
	v_exp_f32_e32 v49, v38
	v_exp_f32_e32 v38, v54
	v_exp_f32_e32 v40, v39
	v_exp_f32_e32 v39, v55
	v_exp_f32_e32 v41, v41
	v_exp_f32_e32 v42, v56
	v_exp_f32_e32 v44, v43
	v_exp_f32_e32 v43, v57
	v_exp_f32_e32 v45, v45
	v_exp_f32_e32 v62, v58
	v_exp_f32_e32 v64, v63
	v_exp_f32_e32 v63, v59
	v_exp_f32_e32 v65, v65
	v_exp_f32_e32 v58, v60
	v_exp_f32_e32 v60, v117
	v_exp_f32_e32 v59, v61
	v_exp_f32_e32 v61, v116
	v_exp_f32_e32 v50, v111
	v_exp_f32_e32 v52, v115
	v_exp_f32_e32 v51, v110
	v_exp_f32_e32 v53, v114
	v_exp_f32_e32 v54, v109
	v_exp_f32_e32 v56, v113
	v_exp_f32_e32 v55, v108
	v_exp_f32_e32 v57, v112
	v_cvt_pk_bf16_f32 v108, v34, v35
	v_cvt_pk_bf16_f32 v109, v46, v47
	v_cvt_pk_bf16_f32 v110, v38, v39
	v_cvt_pk_bf16_f32 v111, v42, v43
	v_cvt_pk_bf16_f32 v112, v62, v63
	v_cvt_pk_bf16_f32 v113, v58, v59
	v_cvt_pk_bf16_f32 v114, v50, v51
	v_cvt_pk_bf16_f32 v115, v54, v55
	v_cvt_pk_bf16_f32 v116, v36, v37
	v_cvt_pk_bf16_f32 v117, v48, v49
	v_cvt_pk_bf16_f32 v118, v40, v41
	v_cvt_pk_bf16_f32 v119, v44, v45
	v_cvt_pk_bf16_f32 v120, v64, v65
	v_cvt_pk_bf16_f32 v121, v60, v61
	v_cvt_pk_bf16_f32 v122, v52, v53
	v_cvt_pk_bf16_f32 v123, v56, v57
	s_setprio 1
	v_add_u32_e32 v124, s17, v181
	ds_read_b64_tr_b16 v[216:217], v124 offset:8192
	ds_read_b64_tr_b16 v[218:219], v124 offset:8704
	ds_read_b64_tr_b16 v[220:221], v124 offset:9216
	ds_read_b64_tr_b16 v[222:223], v124 offset:9728
	s_waitcnt lgkmcnt(2)
	v_mfma_f32_32x32x16_bf16 v[2:17], v[108:111], v[216:219], v[2:17]
	ds_read_b64_tr_b16 v[216:217], v124 offset:10240
	ds_read_b64_tr_b16 v[218:219], v124 offset:10752
	s_waitcnt lgkmcnt(2)
	v_mfma_f32_32x32x16_bf16 v[2:17], v[112:115], v[220:223], v[2:17]
	ds_read_b64_tr_b16 v[220:221], v124 offset:11264
	ds_read_b64_tr_b16 v[222:223], v124 offset:11776
	s_waitcnt lgkmcnt(2)
	v_mfma_f32_32x32x16_bf16 v[2:17], v[116:119], v[216:219], v[2:17]
	ds_read_b64_tr_b16 v[216:217], v124 offset:12288
	ds_read_b64_tr_b16 v[218:219], v124 offset:12800
	s_waitcnt lgkmcnt(2)
	v_mfma_f32_32x32x16_bf16 v[2:17], v[120:123], v[220:223], v[2:17]
	ds_read_b64_tr_b16 v[220:221], v124 offset:13312
	ds_read_b64_tr_b16 v[222:223], v124 offset:13824
	s_waitcnt lgkmcnt(2)
	v_mfma_f32_32x32x16_bf16 v[18:33], v[108:111], v[216:219], v[18:33]
	ds_read_b64_tr_b16 v[216:217], v124 offset:14336
	ds_read_b64_tr_b16 v[218:219], v124 offset:14848
	s_waitcnt lgkmcnt(2)
	v_mfma_f32_32x32x16_bf16 v[18:33], v[112:115], v[220:223], v[18:33]
	ds_read_b64_tr_b16 v[220:221], v124 offset:15360
	ds_read_b64_tr_b16 v[222:223], v124 offset:15872
	s_waitcnt lgkmcnt(2)
	v_mfma_f32_32x32x16_bf16 v[18:33], v[116:119], v[216:219], v[18:33]
	s_waitcnt lgkmcnt(0)
	v_mfma_f32_32x32x16_bf16 v[18:33], v[120:123], v[220:223], v[18:33]
	s_setprio 0
	s_cmp_ge_u32 s13, s48
	s_cselect_b64 s[10:11], -1, 0
	s_and_b64 vcc, exec, s[10:11]
	s_cbranch_vccnz .LBB0_4175
	s_xor_b32 s16, s16, 0x4000
	v_add_u32_e32 v108, s16, v182
	ds_write_b128 v108, v[74:77]
	ds_write_b128 v108, v[78:81] offset:8192
